# INPROJ K-loop: LDS fragment read addresses precomputed per tile as well
# speedup vs baseline: 1.0009x; 1.0009x over previous
; #define PG8_STAGE(bufoff, gbase, voff) do { _Pragma("unroll") for (int _i = 0; _i < 2; ++_i) \
;         __builtin_amdgcn_global_load_lds((const unsigned*)((const char*)(gbase) + (voff)[_i]), (PG8_LAS unsigned*)(lds + (bufoff) + ldsw + _i * 8192), 16, 0, 0); } while (0)
; #define PG8_LDA(dst, b, h) do { _Pragma("unroll") for (int m = 0; m < 4; ++m) _Pragma("unroll") for (int k = 0; k < 2; ++k) dst[m][k] = *(const PG8_LAS bf16x8*)(lds + PG8_SA(b, h) + aoff + m * 2048 + k * 1024); } while (0)
; #define PG8_LDB(dst, b, h) do { _Pragma("unroll") for (int n = 0; n < 2; ++n) _Pragma("unroll") for (int k = 0; k < 2; ++k) dst[n][k] = *(const PG8_LAS bf16x8*)(lds + PG8_SB(b, h) + boff + n * 2048 + k * 1024); } while (0)
; #define PG8_WAIT_V(n) asm volatile("s_waitcnt vmcnt(" #n ")" ::: "memory")
; #define PG8_WAIT_L(n) asm volatile("s_waitcnt lgkmcnt(" #n ")" ::: "memory")
; #define PG8_BAR __builtin_amdgcn_s_barrier()
; #define PG8_SCHED __builtin_amdgcn_sched_barrier(0)
; template <class Epi, class Sched, bool ALIGN_EPI = false, bool SP2 = false>
; __device__ __forceinline__ void gemm_phase(PG8_LAS unsigned char* lds, const Gemm g, const Sched& S, const Epi& E, int wave_in) {
;     ...
;         const char* nA = has_next ? (const char*)g.A + (size_t)nxt.pm * tstepA : cA; const char* nB = has_next ? (const char*)g.Bt + (size_t)nxt.pn * tstep : cB;
;         for (int t = 0; t < nt; t += 2) {
;             const bool last = (t == nt - 2);
;             const char* a1 = cA + (size_t)(t + 1) * kstep;
;             const char* a2 = last ? nA : cA + (size_t)(t + 2) * kstep; const char* b2 = last ? nB : cB + (size_t)(t + 2) * kstep;
;             const char* a3 = a2 + kstep; const char* b3 = b2 + kstep;
;             if (last && has_next) S.a_ready(nxt);
;             if constexpr (SP2) {
;             PG8_LDB(B0, 0, 0); PG8_LDB(B1, 0, 1); PG8_SCHED; PG8_LDA(At, 0, 0); PG8_STAGE(PG8_SA(1, 1), a1 + hstepA, voffA);
;             PG8_WAIT_V(8); PG8_WAIT_L(0); PG8_BAR; PG8_MMA(0, 0, At, B0); PG8_MMA(0, 1, At, B1); PG8_BAR; PG8_SCHED;
;     ...
; #pragma unroll
;         for (int a = 0; a < 2; ++a)
; #pragma unroll
;             for (int b = 0; b < 2; ++b)
; #pragma unroll
;                 for (int m = 0; m < 4; ++m)
; #pragma unroll
;                     for (int n = 0; n < 2; ++n) acc[a][b][m][n] = (f32x4){0.f, 0.f, 0.f, 0.f};
;         cur = nxt; cA = nA; cB = nB; ++ui;
.LBB0_276:
	s_ashr_i32 s19, s18, 31
	s_lshl_b64 s[4:5], s[18:19], 20
	v_readlane_b32 s20, v253, 60
	v_readlane_b32 s21, v253, 61
	s_add_u32 s20, s20, s4
	s_load_dwordx2 s[22:23], s[82:83], 0xf8
	s_addc_u32 s21, s21, s5
	s_and_b64 s[4:5], s[6:7], exec
	s_cselect_b32 s19, s21, s1
	s_cselect_b32 s36, s20, s0
	s_ashr_i32 s17, s16, 31
	s_lshl_b64 s[4:5], s[16:17], 20
	s_waitcnt lgkmcnt(0)
	s_add_u32 s22, s22, s4
	s_addc_u32 s23, s23, s5
	s_and_b64 s[4:5], s[6:7], exec
	s_cselect_b32 s17, s23, s3
	s_cselect_b32 s37, s22, s2
	s_add_u32 s0, s0, 0x80080
	s_addc_u32 s1, s1, 0
	s_add_u32 s38, s2, 0x100
	v_mov_b32_e32 v2, 0
	s_addc_u32 s39, s3, 0
	s_mov_b32 s40, -2
	v_mov_b32_e32 v3, v2
	v_mov_b32_e32 v4, v2
	v_mov_b32_e32 v5, v2
	v_mov_b32_e32 v6, v2
	v_mov_b32_e32 v7, v2
	v_mov_b32_e32 v8, v2
	v_mov_b32_e32 v9, v2
	v_mov_b32_e32 v18, v2
	v_mov_b32_e32 v19, v2
	s_waitcnt vmcnt(0)
	v_mov_b32_e32 v20, v2
	v_mov_b32_e32 v21, v2
	v_mov_b32_e32 v22, v2
	v_mov_b32_e32 v23, v2
	v_mov_b32_e32 v24, v2
	v_mov_b32_e32 v25, v2
	v_mov_b32_e32 v50, v2
	v_mov_b32_e32 v51, v2
	v_mov_b32_e32 v52, v2
	v_mov_b32_e32 v53, v2
	v_mov_b32_e32 v54, v2
	v_mov_b32_e32 v55, v2
	v_mov_b32_e32 v56, v2
	v_mov_b32_e32 v57, v2
	v_mov_b32_e32 v66, v2
	v_mov_b32_e32 v67, v2
	v_mov_b32_e32 v68, v2
	v_mov_b32_e32 v69, v2
	v_mov_b32_e32 v70, v2
	v_mov_b32_e32 v71, v2
	v_mov_b32_e32 v72, v2
	v_mov_b32_e32 v73, v2
	v_mov_b32_e32 v10, v2
	v_mov_b32_e32 v11, v2
	v_mov_b32_e32 v12, v2
	v_mov_b32_e32 v13, v2
	v_mov_b32_e32 v14, v2
	v_mov_b32_e32 v15, v2
	v_mov_b32_e32 v16, v2
	v_mov_b32_e32 v17, v2
	v_mov_b32_e32 v34, v2
	v_mov_b32_e32 v35, v2
	v_mov_b32_e32 v36, v2
	v_mov_b32_e32 v37, v2
	v_mov_b32_e32 v38, v2
	v_mov_b32_e32 v39, v2
	v_mov_b32_e32 v40, v2
	v_mov_b32_e32 v41, v2
	v_mov_b32_e32 v58, v2
	v_mov_b32_e32 v59, v2
	v_mov_b32_e32 v60, v2
	v_mov_b32_e32 v61, v2
	v_mov_b32_e32 v62, v2
	v_mov_b32_e32 v63, v2
	v_mov_b32_e32 v64, v2
	v_mov_b32_e32 v65, v2
	v_mov_b32_e32 v74, v2
	v_mov_b32_e32 v75, v2
	v_mov_b32_e32 v76, v2
	v_mov_b32_e32 v77, v2
	v_mov_b32_e32 v78, v2
	v_mov_b32_e32 v79, v2
	v_mov_b32_e32 v80, v2
	v_mov_b32_e32 v81, v2
	v_mov_b32_e32 v82, v2
	v_mov_b32_e32 v83, v2
	v_mov_b32_e32 v84, v2
	v_mov_b32_e32 v85, v2
	v_mov_b32_e32 v86, v2
	v_mov_b32_e32 v87, v2
	v_mov_b32_e32 v88, v2
	v_mov_b32_e32 v89, v2
	v_mov_b32_e32 v98, v2
	v_mov_b32_e32 v99, v2
	v_mov_b32_e32 v100, v2
	v_mov_b32_e32 v101, v2
	v_mov_b32_e32 v102, v2
	v_mov_b32_e32 v103, v2
	v_mov_b32_e32 v104, v2
	v_mov_b32_e32 v105, v2
	v_mov_b32_e32 v114, v2
	v_mov_b32_e32 v115, v2
	v_mov_b32_e32 v116, v2
	v_mov_b32_e32 v117, v2
	v_mov_b32_e32 v118, v2
	v_mov_b32_e32 v119, v2
	v_mov_b32_e32 v120, v2
	v_mov_b32_e32 v121, v2
	v_mov_b32_e32 v130, v2
	v_mov_b32_e32 v131, v2
	v_mov_b32_e32 v132, v2
	v_mov_b32_e32 v133, v2
	v_mov_b32_e32 v134, v2
	v_mov_b32_e32 v135, v2
	v_mov_b32_e32 v136, v2
	v_mov_b32_e32 v137, v2
	v_mov_b32_e32 v90, v2
	v_mov_b32_e32 v91, v2
	v_mov_b32_e32 v92, v2
	v_mov_b32_e32 v93, v2
	v_mov_b32_e32 v94, v2
	v_mov_b32_e32 v95, v2
	v_mov_b32_e32 v96, v2
	v_mov_b32_e32 v97, v2
	v_mov_b32_e32 v106, v2
	v_mov_b32_e32 v107, v2
	v_mov_b32_e32 v108, v2
	v_mov_b32_e32 v109, v2
	v_mov_b32_e32 v110, v2
	v_mov_b32_e32 v111, v2
	v_mov_b32_e32 v112, v2
	v_mov_b32_e32 v113, v2
	v_mov_b32_e32 v122, v2
	v_mov_b32_e32 v123, v2
	v_mov_b32_e32 v124, v2
	v_mov_b32_e32 v125, v2
	v_mov_b32_e32 v126, v2
	v_mov_b32_e32 v127, v2
	v_mov_b32_e32 v128, v2
	v_mov_b32_e32 v129, v2
	v_mov_b32_e32 v138, v2
	v_mov_b32_e32 v139, v2
	v_mov_b32_e32 v140, v2
	v_mov_b32_e32 v141, v2
	v_mov_b32_e32 v142, v2
	v_mov_b32_e32 v143, v2
	v_mov_b32_e32 v144, v2
	v_mov_b32_e32 v145, v2
	v_add_u32_e32 v240, 0x10000, v181
	v_add_u32_e32 v241, 0x14000, v181
	v_add_u32_e32 v242, 0x18000, v181
	v_add_u32_e32 v243, 0x1c000, v181
	s_nop 0
	s_nop 0
	s_nop 0
	s_nop 0
	s_nop 0
	s_nop 0
.LBB0_277:
	s_add_u32 s2, s0, 0xfff80080
	s_addc_u32 s3, s1, -1
	s_add_i32 s41, 0, 0x10000
	s_cmp_eq_u32 s40, 28
	s_cselect_b32 s5, s19, s3
	s_cselect_b32 s4, s36, s2
	s_cselect_b32 s3, s17, s39
	s_cselect_b32 s2, s37, s38
	s_add_i32 s44, 0, 0x14000
	ds_read_b128 v[26:29], v240
	ds_read_b128 v[30:33], v240 offset:1024
	ds_read_b128 v[42:45], v240 offset:2048
	ds_read_b128 v[46:49], v240 offset:3072
	ds_read_b128 v[168:171], v241
	ds_read_b128 v[172:175], v241 offset:1024
	ds_read_b128 v[176:179], v241 offset:2048
	ds_read_b128 v[184:187], v241 offset:3072
	s_add_i32 m0, s25, 0xc000
	ds_read_b128 v[188:191], v183
	ds_read_b128 v[212:215], v183 offset:1024
	ds_read_b128 v[216:219], v183 offset:2048
	ds_read_b128 v[220:223], v183 offset:3072
	ds_read_b128 v[224:227], v183 offset:4096
	ds_read_b128 v[228:231], v183 offset:5120
	ds_read_b128 v[232:235], v183 offset:6144
	ds_read_b128 v[236:239], v183 offset:7168
	global_load_lds_dwordx4 v152, s[0:1]
	s_add_i32 m0, s25, 0xe000
	s_nop 0
	global_load_lds_dwordx4 v154, s[0:1]
	s_waitcnt vmcnt(8)
	s_waitcnt lgkmcnt(0)
	s_barrier
; #define PG8_STAGE(bufoff, gbase, voff) do { _Pragma("unroll") for (int _i = 0; _i < 2; ++_i) \
;         __builtin_amdgcn_global_load_lds((const unsigned*)((const char*)(gbase) + (voff)[_i]), (PG8_LAS unsigned*)(lds + (bufoff) + ldsw + _i * 8192), 16, 0, 0); } while (0)
; #define PG8_LDA(dst, b, h) do { _Pragma("unroll") for (int m = 0; m < 4; ++m) _Pragma("unroll") for (int k = 0; k < 2; ++k) dst[m][k] = *(const PG8_LAS bf16x8*)(lds + PG8_SA(b, h) + aoff + m * 2048 + k * 1024); } while (0)
; #define PG8_MMA(ai, bj, At, Bt) do { __builtin_amdgcn_s_setprio(1); _Pragma("unroll") for (int m = 0; m < 4; ++m) _Pragma("unroll") for (int n = 0; n < 2; ++n) _Pragma("unroll") for (int k = 0; k < 2; ++k) \
;         acc[ai][bj][m][n] = __builtin_amdgcn_mfma_f32_16x16x32_bf16(Bt[n][k], At[m][k], acc[ai][bj][m][n], 0, 0, 0); __builtin_amdgcn_s_setprio(0); } while (0)
; #define PG8_WAIT_V(n) asm volatile("s_waitcnt vmcnt(" #n ")" ::: "memory")
; #define PG8_WAIT_L(n) asm volatile("s_waitcnt lgkmcnt(" #n ")" ::: "memory")
; #define PG8_BAR __builtin_amdgcn_s_barrier()
; #define PG8_SCHED __builtin_amdgcn_sched_barrier(0)
; template <class Epi, class Sched, bool ALIGN_EPI = false, bool SP2 = false>
; __device__ __forceinline__ void gemm_phase(PG8_LAS unsigned char* lds, const Gemm g, const Sched& S, const Epi& E, int wave_in) {
;     ...
;             PG8_WAIT_V(8); PG8_WAIT_L(0); PG8_BAR; PG8_MMA(0, 0, At, B0); PG8_MMA(0, 1, At, B1); PG8_BAR; PG8_SCHED;
;             PG8_LDA(At, 0, 1); PG8_STAGE(PG8_SB(0, 0), b2, voffB); PG8_STAGE(PG8_SB(0, 1), b2 + hstep, voffB); PG8_STAGE(PG8_SA(0, 0), a2, voffA);
;             PG8_WAIT_V(8); PG8_WAIT_L(0); PG8_BAR; PG8_MMA(1, 0, At, B0); PG8_MMA(1, 1, At, B1); PG8_BAR; PG8_SCHED;
	s_waitcnt lgkmcnt(0)
	v_mfma_f32_16x16x32_bf16 v[142:145], v[26:29], v[188:191], v[142:145]
	v_mfma_f32_16x16x32_bf16 v[138:141], v[42:45], v[188:191], v[138:141]
	v_mfma_f32_16x16x32_bf16 v[126:129], v[26:29], v[216:219], v[126:129]
	v_mfma_f32_16x16x32_bf16 v[122:125], v[42:45], v[216:219], v[122:125]
	v_mfma_f32_16x16x32_bf16 v[110:113], v[26:29], v[224:227], v[110:113]
	v_mfma_f32_16x16x32_bf16 v[106:109], v[42:45], v[224:227], v[106:109]
	v_mfma_f32_16x16x32_bf16 v[94:97], v[26:29], v[232:235], v[94:97]
	v_mfma_f32_16x16x32_bf16 v[90:93], v[42:45], v[232:235], v[90:93]
	v_mfma_f32_16x16x32_bf16 v[142:145], v[30:33], v[212:215], v[142:145]
	v_mfma_f32_16x16x32_bf16 v[138:141], v[46:49], v[212:215], v[138:141]
	v_mfma_f32_16x16x32_bf16 v[126:129], v[30:33], v[220:223], v[126:129]
	v_mfma_f32_16x16x32_bf16 v[122:125], v[46:49], v[220:223], v[122:125]
	v_mfma_f32_16x16x32_bf16 v[110:113], v[30:33], v[228:231], v[110:113]
	v_mfma_f32_16x16x32_bf16 v[106:109], v[46:49], v[228:231], v[106:109]
	v_mfma_f32_16x16x32_bf16 v[94:97], v[30:33], v[236:239], v[94:97]
	v_mfma_f32_16x16x32_bf16 v[90:93], v[46:49], v[236:239], v[90:93]
	v_mfma_f32_16x16x32_bf16 v[134:137], v[168:171], v[188:191], v[134:137]
	v_mfma_f32_16x16x32_bf16 v[130:133], v[176:179], v[188:191], v[130:133]
	v_mfma_f32_16x16x32_bf16 v[118:121], v[168:171], v[216:219], v[118:121]
	v_mfma_f32_16x16x32_bf16 v[114:117], v[176:179], v[216:219], v[114:117]
	v_mfma_f32_16x16x32_bf16 v[102:105], v[168:171], v[224:227], v[102:105]
	v_mfma_f32_16x16x32_bf16 v[98:101], v[176:179], v[224:227], v[98:101]
	v_mfma_f32_16x16x32_bf16 v[86:89], v[168:171], v[232:235], v[86:89]
	v_mfma_f32_16x16x32_bf16 v[82:85], v[176:179], v[232:235], v[82:85]
	v_mfma_f32_16x16x32_bf16 v[134:137], v[172:175], v[212:215], v[134:137]
	v_mfma_f32_16x16x32_bf16 v[130:133], v[184:187], v[212:215], v[130:133]
	v_mfma_f32_16x16x32_bf16 v[118:121], v[172:175], v[220:223], v[118:121]
	v_mfma_f32_16x16x32_bf16 v[114:117], v[184:187], v[220:223], v[114:117]
	v_mfma_f32_16x16x32_bf16 v[102:105], v[172:175], v[228:231], v[102:105]
	v_mfma_f32_16x16x32_bf16 v[98:101], v[184:187], v[228:231], v[98:101]
	v_mfma_f32_16x16x32_bf16 v[86:89], v[172:175], v[236:239], v[86:89]
	v_mfma_f32_16x16x32_bf16 v[82:85], v[184:187], v[236:239], v[82:85]
	s_barrier
	s_add_i32 s41, s41, s24
	s_add_u32 vcc_lo, s2, s84
	s_addc_u32 vcc_hi, s3, s85
	s_mov_b32 m0, s41
	ds_read_b128 v[188:191], v183 offset:16384
	ds_read_b128 v[212:215], v183 offset:17408
	ds_read_b128 v[216:219], v183 offset:18432
	ds_read_b128 v[220:223], v183 offset:19456
	ds_read_b128 v[224:227], v183 offset:20480
	ds_read_b128 v[228:231], v183 offset:21504
	ds_read_b128 v[232:235], v183 offset:22528
	ds_read_b128 v[236:239], v183 offset:23552
	global_load_lds_dwordx4 v0, s[2:3]
	s_add_i32 m0, s41, 0x2000
	s_add_u32 s42, s2, 0x80000
	s_addc_u32 s43, s3, 0
	s_add_i32 s41, s44, s24
	global_load_lds_dwordx4 v146, s[2:3]
	s_mov_b32 m0, s41
	s_add_u32 s98, s4, s84
	s_addc_u32 s99, s5, s85
	global_load_lds_dwordx4 v0, s[42:43]
	s_add_i32 m0, s41, 0x2000
	s_nop 0
	global_load_lds_dwordx4 v146, s[42:43]
	s_mov_b32 m0, s25
	s_nop 0
	global_load_lds_dwordx4 v150, s[4:5]
	s_mov_b32 m0, s26
	s_nop 0
	global_load_lds_dwordx4 v148, s[4:5]
	s_waitcnt vmcnt(8)
	s_waitcnt lgkmcnt(0)
	s_barrier
	s_waitcnt lgkmcnt(0)
	v_mfma_f32_16x16x32_bf16 v[78:81], v[26:29], v[188:191], v[78:81]
	v_mfma_f32_16x16x32_bf16 v[74:77], v[42:45], v[188:191], v[74:77]
	v_mfma_f32_16x16x32_bf16 v[62:65], v[26:29], v[216:219], v[62:65]
	v_mfma_f32_16x16x32_bf16 v[58:61], v[42:45], v[216:219], v[58:61]
	v_mfma_f32_16x16x32_bf16 v[38:41], v[26:29], v[224:227], v[38:41]
	v_mfma_f32_16x16x32_bf16 v[34:37], v[42:45], v[224:227], v[34:37]
	v_mfma_f32_16x16x32_bf16 v[14:17], v[26:29], v[232:235], v[14:17]
	v_mfma_f32_16x16x32_bf16 v[10:13], v[42:45], v[232:235], v[10:13]
	v_mfma_f32_16x16x32_bf16 v[78:81], v[30:33], v[212:215], v[78:81]
	v_mfma_f32_16x16x32_bf16 v[74:77], v[46:49], v[212:215], v[74:77]
	v_mfma_f32_16x16x32_bf16 v[62:65], v[30:33], v[220:223], v[62:65]
	v_mfma_f32_16x16x32_bf16 v[58:61], v[46:49], v[220:223], v[58:61]
	v_mfma_f32_16x16x32_bf16 v[38:41], v[30:33], v[228:231], v[38:41]
	v_mfma_f32_16x16x32_bf16 v[34:37], v[46:49], v[228:231], v[34:37]
	v_mfma_f32_16x16x32_bf16 v[14:17], v[30:33], v[236:239], v[14:17]
	v_mfma_f32_16x16x32_bf16 v[10:13], v[46:49], v[236:239], v[10:13]
	v_mfma_f32_16x16x32_bf16 v[22:25], v[168:171], v[224:227], v[22:25]
	v_mfma_f32_16x16x32_bf16 v[18:21], v[176:179], v[224:227], v[18:21]
	v_mfma_f32_16x16x32_bf16 v[6:9], v[168:171], v[232:235], v[6:9]
	v_mfma_f32_16x16x32_bf16 v[2:5], v[176:179], v[232:235], v[2:5]
	v_mfma_f32_16x16x32_bf16 v[26:29], v[168:171], v[188:191], v[70:73]
	v_mfma_f32_16x16x32_bf16 v[30:33], v[176:179], v[188:191], v[66:69]
	v_mfma_f32_16x16x32_bf16 v[42:45], v[168:171], v[216:219], v[54:57]
	v_mfma_f32_16x16x32_bf16 v[46:49], v[176:179], v[216:219], v[50:53]
	v_mfma_f32_16x16x32_bf16 v[22:25], v[172:175], v[228:231], v[22:25]
	v_mfma_f32_16x16x32_bf16 v[18:21], v[184:187], v[228:231], v[18:21]
	v_mfma_f32_16x16x32_bf16 v[6:9], v[172:175], v[236:239], v[6:9]
	v_mfma_f32_16x16x32_bf16 v[2:5], v[184:187], v[236:239], v[2:5]
	v_mfma_f32_16x16x32_bf16 v[26:29], v[172:175], v[212:215], v[26:29]
	v_mfma_f32_16x16x32_bf16 v[30:33], v[184:187], v[212:215], v[30:33]
	v_mfma_f32_16x16x32_bf16 v[42:45], v[172:175], v[220:223], v[42:45]
	v_mfma_f32_16x16x32_bf16 v[46:49], v[184:187], v[220:223], v[46:49]
	s_barrier
; #define PG8_STAGE(bufoff, gbase, voff) do { _Pragma("unroll") for (int _i = 0; _i < 2; ++_i) \
;         __builtin_amdgcn_global_load_lds((const unsigned*)((const char*)(gbase) + (voff)[_i]), (PG8_LAS unsigned*)(lds + (bufoff) + ldsw + _i * 8192), 16, 0, 0); } while (0)
; #define PG8_LDA(dst, b, h) do { _Pragma("unroll") for (int m = 0; m < 4; ++m) _Pragma("unroll") for (int k = 0; k < 2; ++k) dst[m][k] = *(const PG8_LAS bf16x8*)(lds + PG8_SA(b, h) + aoff + m * 2048 + k * 1024); } while (0)
; #define PG8_LDB(dst, b, h) do { _Pragma("unroll") for (int n = 0; n < 2; ++n) _Pragma("unroll") for (int k = 0; k < 2; ++k) dst[n][k] = *(const PG8_LAS bf16x8*)(lds + PG8_SB(b, h) + boff + n * 2048 + k * 1024); } while (0)
; #define PG8_MMA(ai, bj, At, Bt) do { __builtin_amdgcn_s_setprio(1); _Pragma("unroll") for (int m = 0; m < 4; ++m) _Pragma("unroll") for (int n = 0; n < 2; ++n) _Pragma("unroll") for (int k = 0; k < 2; ++k) \
;         acc[ai][bj][m][n] = __builtin_amdgcn_mfma_f32_16x16x32_bf16(Bt[n][k], At[m][k], acc[ai][bj][m][n], 0, 0, 0); __builtin_amdgcn_s_setprio(0); } while (0)
; #define PG8_WAIT_V(n) asm volatile("s_waitcnt vmcnt(" #n ")" ::: "memory")
; #define PG8_WAIT_L(n) asm volatile("s_waitcnt lgkmcnt(" #n ")" ::: "memory")
; #define PG8_BAR __builtin_amdgcn_s_barrier()
; template <class Epi, class Sched, bool ALIGN_EPI = false, bool SP2 = false>
; __device__ __forceinline__ void gemm_phase(PG8_LAS unsigned char* lds, const Gemm g, const Sched& S, const Epi& E, int wave_in) {
;     ...
;         for (int t = 0; t < nt; t += 2) {
;             const bool last = (t == nt - 2);
;             const char* a1 = cA + (size_t)(t + 1) * kstep;
;             const char* a2 = last ? nA : cA + (size_t)(t + 2) * kstep; const char* b2 = last ? nB : cB + (size_t)(t + 2) * kstep;
;             const char* a3 = a2 + kstep; const char* b3 = b2 + kstep;
;     ...
;             PG8_LDB(B0, 1, 0); PG8_LDB(B1, 1, 1); PG8_SCHED; PG8_LDA(At, 1, 0); PG8_STAGE(PG8_SA(0, 1), a2 + hstepA, voffA);
;             PG8_WAIT_V(8); PG8_WAIT_L(0); PG8_BAR; PG8_MMA(0, 0, At, B0); PG8_MMA(0, 1, At, B1); PG8_BAR; PG8_SCHED;
;             PG8_LDA(At, 1, 1); PG8_STAGE(PG8_SB(1, 0), b3, voffB); PG8_STAGE(PG8_SB(1, 1), b3 + hstep, voffB); PG8_STAGE(PG8_SA(1, 0), a3, voffA);
;             PG8_WAIT_V(8); PG8_WAIT_L(0); PG8_BAR; PG8_MMA(1, 0, At, B0); PG8_MMA(1, 1, At, B1); PG8_BAR; PG8_SCHED;
	s_add_i32 s41, 0, 0x18000
	s_add_i32 s42, 0, 0x1c000
	ds_read_b128 v[50:53], v242
	ds_read_b128 v[54:57], v242 offset:1024
	ds_read_b128 v[66:69], v242 offset:2048
	ds_read_b128 v[70:73], v242 offset:3072
	ds_read_b128 v[168:171], v243
	ds_read_b128 v[172:175], v243 offset:1024
	ds_read_b128 v[176:179], v243 offset:2048
	ds_read_b128 v[184:187], v243 offset:3072
	s_add_u32 s4, s4, 0x80000
	s_addc_u32 s5, s5, 0
	s_mov_b32 m0, s27
	ds_read_b128 v[188:191], v183 offset:32768
	ds_read_b128 v[212:215], v183 offset:33792
	ds_read_b128 v[216:219], v183 offset:34816
	ds_read_b128 v[220:223], v183 offset:35840
	ds_read_b128 v[224:227], v183 offset:36864
	ds_read_b128 v[228:231], v183 offset:37888
	ds_read_b128 v[232:235], v183 offset:38912
	ds_read_b128 v[236:239], v183 offset:39936
	global_load_lds_dwordx4 v150, s[4:5]
	s_mov_b32 m0, s28
	s_nop 0
	global_load_lds_dwordx4 v148, s[4:5]
	s_waitcnt vmcnt(8)
	s_waitcnt lgkmcnt(0)
	s_barrier
	s_waitcnt lgkmcnt(0)
	v_mfma_f32_16x16x32_bf16 v[142:145], v[50:53], v[188:191], v[142:145]
	v_mfma_f32_16x16x32_bf16 v[138:141], v[66:69], v[188:191], v[138:141]
	v_mfma_f32_16x16x32_bf16 v[126:129], v[50:53], v[216:219], v[126:129]
	v_mfma_f32_16x16x32_bf16 v[122:125], v[66:69], v[216:219], v[122:125]
	v_mfma_f32_16x16x32_bf16 v[110:113], v[50:53], v[224:227], v[110:113]
	v_mfma_f32_16x16x32_bf16 v[106:109], v[66:69], v[224:227], v[106:109]
	v_mfma_f32_16x16x32_bf16 v[94:97], v[50:53], v[232:235], v[94:97]
	v_mfma_f32_16x16x32_bf16 v[90:93], v[66:69], v[232:235], v[90:93]
	v_mfma_f32_16x16x32_bf16 v[142:145], v[54:57], v[212:215], v[142:145]
	v_mfma_f32_16x16x32_bf16 v[138:141], v[70:73], v[212:215], v[138:141]
	v_mfma_f32_16x16x32_bf16 v[126:129], v[54:57], v[220:223], v[126:129]
	v_mfma_f32_16x16x32_bf16 v[122:125], v[70:73], v[220:223], v[122:125]
	v_mfma_f32_16x16x32_bf16 v[110:113], v[54:57], v[228:231], v[110:113]
	v_mfma_f32_16x16x32_bf16 v[106:109], v[70:73], v[228:231], v[106:109]
	v_mfma_f32_16x16x32_bf16 v[94:97], v[54:57], v[236:239], v[94:97]
	v_mfma_f32_16x16x32_bf16 v[90:93], v[70:73], v[236:239], v[90:93]
	v_mfma_f32_16x16x32_bf16 v[134:137], v[168:171], v[188:191], v[134:137]
	v_mfma_f32_16x16x32_bf16 v[130:133], v[176:179], v[188:191], v[130:133]
	v_mfma_f32_16x16x32_bf16 v[118:121], v[168:171], v[216:219], v[118:121]
	v_mfma_f32_16x16x32_bf16 v[114:117], v[176:179], v[216:219], v[114:117]
	v_mfma_f32_16x16x32_bf16 v[102:105], v[168:171], v[224:227], v[102:105]
	v_mfma_f32_16x16x32_bf16 v[98:101], v[176:179], v[224:227], v[98:101]
	v_mfma_f32_16x16x32_bf16 v[86:89], v[168:171], v[232:235], v[86:89]
	v_mfma_f32_16x16x32_bf16 v[82:85], v[176:179], v[232:235], v[82:85]
	v_mfma_f32_16x16x32_bf16 v[134:137], v[172:175], v[212:215], v[134:137]
	v_mfma_f32_16x16x32_bf16 v[130:133], v[184:187], v[212:215], v[130:133]
	v_mfma_f32_16x16x32_bf16 v[118:121], v[172:175], v[220:223], v[118:121]
	v_mfma_f32_16x16x32_bf16 v[114:117], v[184:187], v[220:223], v[114:117]
	v_mfma_f32_16x16x32_bf16 v[102:105], v[172:175], v[228:231], v[102:105]
	v_mfma_f32_16x16x32_bf16 v[98:101], v[184:187], v[228:231], v[98:101]
	v_mfma_f32_16x16x32_bf16 v[86:89], v[172:175], v[236:239], v[86:89]
	v_mfma_f32_16x16x32_bf16 v[82:85], v[184:187], v[236:239], v[82:85]
	s_barrier
	s_add_i32 s4, s41, s24
	s_mov_b32 m0, s4
	ds_read_b128 v[188:191], v183 offset:49152
	ds_read_b128 v[212:215], v183 offset:50176
	ds_read_b128 v[216:219], v183 offset:51200
	ds_read_b128 v[220:223], v183 offset:52224
	ds_read_b128 v[224:227], v183 offset:53248
	ds_read_b128 v[228:231], v183 offset:54272
	ds_read_b128 v[232:235], v183 offset:55296
	ds_read_b128 v[236:239], v183 offset:56320
	global_load_lds_dwordx4 v0, vcc
	s_add_i32 m0, s4, 0x2000
	s_add_u32 s2, s2, 0x80080
	s_addc_u32 s3, s3, 0
	s_add_i32 s4, s42, s24
	global_load_lds_dwordx4 v146, vcc
	s_mov_b32 m0, s4
	s_nop 0
	global_load_lds_dwordx4 v0, s[2:3]
	s_add_i32 m0, s4, 0x2000
	s_nop 0
	global_load_lds_dwordx4 v146, s[2:3]
	s_mov_b32 m0, s29
	s_nop 0
	global_load_lds_dwordx4 v150, s[98:99]
	s_mov_b32 m0, s30
	s_nop 0
	global_load_lds_dwordx4 v148, s[98:99]
	s_waitcnt vmcnt(8)
	s_waitcnt lgkmcnt(0)
	s_barrier
	s_waitcnt lgkmcnt(0)
	v_mfma_f32_16x16x32_bf16 v[78:81], v[50:53], v[188:191], v[78:81]
	v_mfma_f32_16x16x32_bf16 v[74:77], v[66:69], v[188:191], v[74:77]
	v_mfma_f32_16x16x32_bf16 v[62:65], v[50:53], v[216:219], v[62:65]
	v_mfma_f32_16x16x32_bf16 v[58:61], v[66:69], v[216:219], v[58:61]
	v_mfma_f32_16x16x32_bf16 v[38:41], v[50:53], v[224:227], v[38:41]
	v_mfma_f32_16x16x32_bf16 v[34:37], v[66:69], v[224:227], v[34:37]
	v_mfma_f32_16x16x32_bf16 v[14:17], v[50:53], v[232:235], v[14:17]
	v_mfma_f32_16x16x32_bf16 v[10:13], v[66:69], v[232:235], v[10:13]
	v_mfma_f32_16x16x32_bf16 v[78:81], v[54:57], v[212:215], v[78:81]
	v_mfma_f32_16x16x32_bf16 v[74:77], v[70:73], v[212:215], v[74:77]
	v_mfma_f32_16x16x32_bf16 v[62:65], v[54:57], v[220:223], v[62:65]
	v_mfma_f32_16x16x32_bf16 v[58:61], v[70:73], v[220:223], v[58:61]
	v_mfma_f32_16x16x32_bf16 v[38:41], v[54:57], v[228:231], v[38:41]
	v_mfma_f32_16x16x32_bf16 v[34:37], v[70:73], v[228:231], v[34:37]
	v_mfma_f32_16x16x32_bf16 v[14:17], v[54:57], v[236:239], v[14:17]
	v_mfma_f32_16x16x32_bf16 v[10:13], v[70:73], v[236:239], v[10:13]
	v_mfma_f32_16x16x32_bf16 v[26:29], v[168:171], v[188:191], v[26:29]
	v_mfma_f32_16x16x32_bf16 v[70:73], v[172:175], v[212:215], v[26:29]
	v_mfma_f32_16x16x32_bf16 v[26:29], v[176:179], v[188:191], v[30:33]
	v_mfma_f32_16x16x32_bf16 v[66:69], v[184:187], v[212:215], v[26:29]
	v_mfma_f32_16x16x32_bf16 v[26:29], v[168:171], v[216:219], v[42:45]
	v_mfma_f32_16x16x32_bf16 v[54:57], v[172:175], v[220:223], v[26:29]
	v_mfma_f32_16x16x32_bf16 v[26:29], v[176:179], v[216:219], v[46:49]
	v_mfma_f32_16x16x32_bf16 v[22:25], v[168:171], v[224:227], v[22:25]
	v_mfma_f32_16x16x32_bf16 v[18:21], v[176:179], v[224:227], v[18:21]
	v_mfma_f32_16x16x32_bf16 v[6:9], v[168:171], v[232:235], v[6:9]
	v_mfma_f32_16x16x32_bf16 v[2:5], v[176:179], v[232:235], v[2:5]
	v_mfma_f32_16x16x32_bf16 v[50:53], v[184:187], v[220:223], v[26:29]
	v_mfma_f32_16x16x32_bf16 v[22:25], v[172:175], v[228:231], v[22:25]
	v_mfma_f32_16x16x32_bf16 v[18:21], v[184:187], v[228:231], v[18:21]
	v_mfma_f32_16x16x32_bf16 v[6:9], v[172:175], v[236:239], v[6:9]
	v_mfma_f32_16x16x32_bf16 v[2:5], v[184:187], v[236:239], v[2:5]
	s_barrier
	s_add_i32 s40, s40, 2
	s_add_u32 s0, s0, 0x100
	s_addc_u32 s1, s1, 0
	s_add_u32 s38, s38, 0x100
	s_addc_u32 s39, s39, 0
	s_cmp_gt_u32 s40, 29
	s_cbranch_scc0 .LBB0_277
	s_and_b64 vcc, exec, s[14:15]
	s_cbranch_vccz .LBB0_280
	s_barrier
